# v34 plus FFN-up epilogue: second batch of row-stat/scale loads issued with the first; first conv-weight load group issued before the LDS-exchange barrier
# speedup vs baseline: 1.0178x; 1.0006x over previous
; #define PG8_LAS __attribute__((address_space(3)))
; __device__ __forceinline__ float rstd2048(const stat_t* rs, int row) { return rsqrtf((float)rs[row] * (STAT_INV / 2048.0f) + NORM_EPS); }
;     __device__ __forceinline__ void operator()(const f32x4 (&acc)[2][2][4][2], const Unit& u, int wr, int wc, int fr_, int fq_) const {
;     ...
;         f32x4 swv[2][2];
; #pragma unroll
;         for (int bj = 0; bj < 2; ++bj)
; #pragma unroll
;             for (int n = 0; n < 2; ++n) swv[bj][n] = *(const f32x4*)(sw + u.pn * BM + bj * HALF + wc * 32 + 8 * fq + 4 * n);
; #pragma unroll
;         for (int ai = 0; ai < 2; ++ai)
; #pragma unroll
;             for (int m = 0; m < 4; ++m) { const float r = rstd2048(rs, rowb + ai * HALF + m) * sx[rowb + ai * HALF + m];
; #pragma unroll
;                 for (int bj = 0; bj < 2; ++bj)
; #pragma unroll
;                     for (int n = 0; n < 2; ++n) { typedef int i32x4 __attribute__((ext_vector_type(4)));
;                         z[ai][bj][m][n] = __builtin_convertvector(__builtin_bit_cast(i32x4, acc[ai][bj][m][n]), f32x4) * (swv[bj][n] * r); } }
;         PG8_LAS f32x4* X4 = (PG8_LAS f32x4*)xch;
;     ...
; #pragma unroll
;         for (int ai = 0; ai < 2; ++ai) {
;             if (fr == 0) {
; #pragma unroll
;                 for (int bj = 0; bj < 2; ++bj)
; #pragma unroll
;                     for (int n = 0; n < 2; ++n) X4[XIDX(wr, ai, 0) + bj * 2 + n] = z[ai][bj][0][n]; }
;             if (fr == 15) {
; #pragma unroll
;                 for (int bj = 0; bj < 2; ++bj)
; #pragma unroll
;                     for (int n = 0; n < 2; ++n) X4[XIDX(wr, ai, 1) + bj * 2 + n] = z[ai][bj][3][n]; }
.LBB0_83:
	s_lshl_b32 s66, s70, 8
	s_ashr_i32 s67, s66, 31
	v_mov_b32_e32 v174, v240
	v_mov_b32_e32 v175, v241
	s_lshl_b64 s[0:1], s[66:67], 2
	v_readlane_b32 s4, v255, 3
	s_add_u32 s0, s4, s0
	v_readlane_b32 s4, v255, 4
	v_lshlrev_b32_e32 v168, 3, v175
	s_addc_u32 s1, s4, s1
	v_ashrrev_i32_e32 v169, 31, v168
	v_lshl_add_u64 v[34:35], v[168:169], 2, s[0:1]
	s_lshl_b32 s0, s10, 8
	v_readlane_b32 s1, v254, 61
	s_add_i32 s0, s0, s1
	v_lshl_add_u32 v220, v174, 2, s0
	v_readlane_b32 s0, v254, 59
	v_ashrrev_i32_e32 v221, 31, v220
	v_readlane_b32 s1, v254, 60
	global_load_dwordx4 v[18:21], v[34:35], off offset:16
	global_load_dwordx4 v[38:41], v[34:35], off
	global_load_dwordx4 v[22:25], v[34:35], off offset:528
	s_nop 0
	global_load_dwordx4 v[34:37], v[34:35], off offset:512
	v_lshl_add_u64 v[172:173], v[220:221], 3, s[0:1]
	global_load_dwordx4 v[154:157], v[172:173], off offset:16
	global_load_dwordx4 v[164:167], v[172:173], off
	global_load_dwordx4 v[176:179], v[172:173], off offset:1040
	global_load_dwordx4 v[180:183], v[172:173], off offset:1024
	v_readlane_b32 s0, v252, 39
	v_readlane_b32 s1, v252, 40
	v_cvt_f32_i32_e32 v95, v95
	v_cvt_f32_i32_e32 v94, v94
	v_lshl_add_u64 v[170:171], v[220:221], 2, s[0:1]
	global_load_dwordx4 v[158:161], v[170:171], off
	global_load_dwordx4 v[184:187], v[170:171], off offset:512
	v_cvt_f32_i32_e32 v97, v97
	v_cvt_f32_i32_e32 v96, v96
	v_cvt_f32_i32_e32 v59, v59
	v_cvt_f32_i32_e32 v58, v58
	v_cvt_f32_i32_e32 v61, v61
	v_cvt_f32_i32_e32 v60, v60
	v_cvt_f32_i32_e32 v79, v79
	v_cvt_f32_i32_e32 v78, v78
	v_cvt_f32_i32_e32 v81, v81
	v_cvt_f32_i32_e32 v80, v80
	v_cvt_f32_i32_e32 v63, v63
	v_cvt_f32_i32_e32 v62, v62
	v_cvt_f32_i32_e32 v65, v65
	v_cvt_f32_i32_e32 v64, v64
	v_lshlrev_b32_e32 v205, 6, v175
	v_cmp_lt_i32_e64 s[12:13], 14, v174
	s_mov_b64 s[6:7], 0
	s_waitcnt vmcnt(0)
	v_ffbh_u32_e32 v130, v165
	v_min_u32_e32 v132, 32, v130
	v_lshlrev_b64 v[130:131], v132, v[164:165]
	v_min_u32_e32 v130, 1, v130
	v_or_b32_e32 v130, v131, v130
	v_cvt_f32_u32_e32 v130, v130
	v_sub_u32_e32 v131, 32, v132
	v_ldexp_f32 v130, v130, v131
	v_fmamk_f32 v169, v130, 0x2e000000, v204
	v_ffbh_u32_e32 v130, v157
	v_min_u32_e32 v132, 32, v130
	v_lshlrev_b64 v[130:131], v132, v[156:157]
	v_min_u32_e32 v130, 1, v130
	v_or_b32_e32 v130, v131, v130
	v_cvt_f32_u32_e32 v130, v130
	v_sub_u32_e32 v131, 32, v132
	v_cmp_gt_f32_e32 vcc, s17, v169
	v_ldexp_f32 v130, v130, v131
	v_fmamk_f32 v130, v130, 0x2e000000, v204
	v_cmp_gt_f32_e64 s[0:1], s17, v130
	v_mul_f32_e32 v131, 0x4b800000, v130
	s_nop 0
	v_cndmask_b32_e64 v130, v130, v131, s[0:1]
	v_rsq_f32_e32 v130, v130
	s_nop 0
	v_mul_f32_e32 v131, 0x45800000, v130
	v_cndmask_b32_e64 v130, v130, v131, s[0:1]
	v_mul_f32_e32 v156, v161, v130
	v_pk_mul_f32 v[130:131], v[38:39], v[156:157] op_sel_hi:[1,0]
	v_pk_mul_f32 v[132:133], v[40:41], v[156:157] op_sel_hi:[1,0]
	v_pk_mul_f32 v[130:131], v[130:131], v[94:95]
	v_pk_mul_f32 v[132:133], v[132:133], v[96:97]
	v_pk_mul_f32 v[94:95], v[18:19], v[156:157] op_sel_hi:[1,0]
	v_pk_mul_f32 v[96:97], v[20:21], v[156:157] op_sel_hi:[1,0]
	v_pk_mul_f32 v[58:59], v[94:95], v[58:59]
	v_pk_mul_f32 v[60:61], v[96:97], v[60:61]
	v_pk_mul_f32 v[94:95], v[34:35], v[156:157] op_sel_hi:[1,0]
	v_pk_mul_f32 v[96:97], v[36:37], v[156:157] op_sel_hi:[1,0]
	v_pk_mul_f32 v[134:135], v[94:95], v[78:79]
	v_pk_mul_f32 v[136:137], v[96:97], v[80:81]
	v_pk_mul_f32 v[78:79], v[22:23], v[156:157] op_sel_hi:[1,0]
	v_pk_mul_f32 v[80:81], v[24:25], v[156:157] op_sel_hi:[1,0]
	v_pk_mul_f32 v[62:63], v[78:79], v[62:63]
	v_pk_mul_f32 v[64:65], v[80:81], v[64:65]
	v_mov_b64_e32 v[162:163], v[176:177]
	v_mov_b64_e32 v[164:165], v[178:179]
	v_mov_b64_e32 v[78:79], v[180:181]
	v_mov_b64_e32 v[80:81], v[182:183]
	v_ffbh_u32_e32 v94, v79
	v_min_u32_e32 v94, 32, v94
	v_lshlrev_b64 v[78:79], v94, v[78:79]
	v_min_u32_e32 v78, 1, v78
	v_or_b32_e32 v78, v79, v78
	v_sub_u32_e32 v79, 32, v94
	v_mov_b64_e32 v[94:95], v[184:185]
	v_mov_b64_e32 v[96:97], v[186:187]
	v_cvt_f32_u32_e32 v78, v78
	v_ldexp_f32 v78, v78, v79
	v_ffbh_u32_e32 v79, v165
	v_min_u32_e32 v79, 32, v79
	v_lshlrev_b64 v[156:157], v79, v[164:165]
	v_min_u32_e32 v156, 1, v156
	v_or_b32_e32 v156, v157, v156
	v_cvt_f32_u32_e32 v156, v156
	v_sub_u32_e32 v79, 32, v79
	v_fmamk_f32 v78, v78, 0x2e000000, v204
	v_cmp_gt_f32_e64 s[0:1], s17, v78
	v_ldexp_f32 v79, v156, v79
	v_fmamk_f32 v79, v79, 0x2e000000, v204
	v_cmp_gt_f32_e64 s[8:9], s17, v79
	s_and_saveexec_b64 s[82:83], s[12:13]
	s_xor_b64 s[96:97], exec, s[82:83]
	s_cbranch_execz .LBB0_87
	v_cmp_eq_u32_e64 s[12:13], 15, v174
	s_and_saveexec_b64 s[82:83], s[12:13]
	s_cbranch_execz .LBB0_86
	v_readlane_b32 s4, v255, 6
	s_mov_b64 s[6:7], exec
	s_nop 0
	v_add_u32_e32 v156, s4, v205
	ds_write_b128 v156, v[130:133] offset:256
	ds_write_b128 v156, v[58:61] offset:272
	ds_write_b128 v156, v[134:137] offset:288
	ds_write_b128 v156, v[62:65] offset:304

;     __device__ __forceinline__ void operator()(const f32x4 (&acc)[2][2][4][2], const Unit& u, int wr, int wc, int fr_, int fq_) const {
;     ...
;         asm volatile("s_waitcnt lgkmcnt(0)" ::: "memory"); __builtin_amdgcn_s_barrier(); asm volatile("" ::: "memory");
;         const int ch0 = u.pn * HALF + wc * 32 + 8 * fq;
;         const f32x4 zero4 = (f32x4){0.f, 0.f, 0.f, 0.f};
; #pragma unroll
;         for (int ai = 0; ai < 2; ++ai) {
;             unsigned ow[4][4];
; #pragma unroll
;             for (int n = 0; n < 2; ++n) {
;                 const int ch = ch0 + 4 * n;
;                 const f32x4 w0g = *(const f32x4*)(cw + ch), w1g = *(const f32x4*)(cw + NZ_ + ch), w2g = *(const f32x4*)(cw + 2 * NZ_ + ch), bg = *(const f32x4*)(cb + ch);
;                 const f32x4 w0u = *(const f32x4*)(cw + DFF_ + ch), w1u = *(const f32x4*)(cw + NZ_ + DFF_ + ch), w2u = *(const f32x4*)(cw + 2 * NZ_ + DFF_ + ch), bu = *(const f32x4*)(cb + DFF_ + ch);
;                 f32x4 pBg = zero4, pBu = zero4, nBg = zero4, nBu = zero4;
;                 if (wr == 1) { pBg = X4[XIDX(0, ai, 1) + n]; pBu = X4[XIDX(0, ai, 1) + 2 + n]; }
;                 else if (ai == 1) { pBg = X4[XIDX(1, 0, 1) + n]; pBu = X4[XIDX(1, 0, 1) + 2 + n]; }
;                 if (wr == 0) { nBg = X4[XIDX(1, ai, 0) + n]; nBu = X4[XIDX(1, ai, 0) + 2 + n]; }
;                 else if (ai == 0) { nBg = X4[XIDX(0, 1, 0) + n]; nBu = X4[XIDX(0, 1, 0) + 2 + n]; }
.LBB0_101:
	s_or_b64 exec, exec, s[0:1]
	s_lshl_b32 s0, s70, 7
	s_or_b32 s0, s0, s36
	v_add_u32_e32 v236, s0, v168
	v_ashrrev_i32_e32 v237, 31, v236
	v_readlane_b32 s0, v255, 8
	v_lshlrev_b64 v[96:97], 2, v[236:237]
	v_readlane_b32 s1, v255, 9
	v_lshl_add_u64 v[226:227], s[50:51], 0, v[96:97]
	v_lshl_add_u64 v[78:79], s[0:1], 0, v[96:97]
	v_readlane_b32 s0, v255, 10
	v_readlane_b32 s1, v255, 11
	v_lshl_add_u64 v[228:229], s[44:45], 0, v[96:97]
	v_lshl_add_u64 v[232:233], s[42:43], 0, v[96:97]
	v_lshl_add_u64 v[222:223], s[0:1], 0, v[96:97]
	v_lshl_add_u64 v[234:235], s[48:49], 0, v[96:97]
	v_lshl_add_u64 v[224:225], s[18:19], 0, v[96:97]
	global_load_dwordx4 v[166:169], v[78:79], off
	global_load_dwordx4 v[174:177], v[224:225], off
	global_load_dwordx4 v[182:185], v[226:227], off
	global_load_dwordx4 v[190:193], v[222:223], off
	v_lshl_add_u64 v[230:231], s[20:21], 0, v[96:97]
	global_load_dwordx4 v[162:165], v[228:229], off
	global_load_dwordx4 v[170:173], v[230:231], off
	global_load_dwordx4 v[178:181], v[232:233], off
	global_load_dwordx4 v[186:189], v[234:235], off
	s_waitcnt lgkmcnt(0)
	s_barrier
	v_readlane_b32 s0, v255, 7
	v_cndmask_b32_e64 v96, 0, 1, s[46:47]
	v_mov_b32_e32 v221, 0x8800
	v_mov_b32_e32 v207, 0x2000
	v_mov_b32_e32 v202, v246
	v_mov_b32_e32 v206, 1
	v_add_u32_e32 v94, s0, v205
	v_mov_b32_e32 v102, 0
	v_cmp_ne_u32_e64 s[8:9], 1, v96
	s_andn2_b64 vcc, exec, s[46:47]
	v_mov_b32_e32 v194, 0
	v_mov_b32_e32 v195, 0
	v_mov_b32_e32 v196, 0
	v_mov_b32_e32 v197, 0
	v_mov_b32_e32 v198, 0
	v_mov_b32_e32 v199, 0
	v_mov_b32_e32 v200, 0
	v_mov_b32_e32 v201, 0
	s_cbranch_vccnz .LBB0_103
	ds_read_b128 v[198:201], v94 offset:256
	ds_read_b128 v[194:197], v94 offset:288
